# relocate X1B/H/PP into each batch's own (dead) Z rows so no cross-XCD aliasing remains; P3->P4 barrier becomes XCD-local too
# speedup vs baseline: 1.0005x; 1.0005x over previous
.Lstag4_done:
	s_cmp_eq_u32 s99, 0
	s_cbranch_scc1 .Lx1b_done
	s_and_b32 s100, s2, 7
	s_mul_i32 s100, s100, 0x2400000
	s_add_u32 s40, s40, s100
	s_addc_u32 s41, s41, 0

.LBB0_800:
	s_add_u32 s61, s76, 0x7c00800
	s_addc_u32 s62, s77, 0
	s_add_u32 s63, s76, 0x1000800
	s_addc_u32 s64, s77, 0
	s_and_b32 s100, s2, 7
	s_mul_i32 s100, s100, 0x1600000
	s_add_u32 s100, s100, 0x8400000
	s_cmp_eq_u32 s99, 0
	s_cselect_b32 s100, 0xbc00000, s100
	s_add_u32 s12, s76, s100
	s_addc_u32 s13, s77, 0
	s_lshl_b32 s14, s14, 5
	s_and_b32 s20, s14, 0x60
	s_mov_b64 s[14:15], 0x80
	s_add_i32 m0, s57, 0x18000
	v_lshl_add_u64 v[6:7], v[6:7], 0, s[14:15]
	s_waitcnt vmcnt(2)
	s_barrier
	global_load_lds_dwordx4 v[6:7], off
	v_lshl_add_u64 v[4:5], v[4:5], 0, s[14:15]
	s_add_i32 m0, s57, 0x1a000
	s_add_i32 s65, s57, 0x8000
	s_lshl_b32 s16, s8, 13
	s_lshl_b32 s18, s20, 7
	global_load_lds_dwordx4 v[4:5], off
	v_lshl_add_u64 v[0:1], v[0:1], 0, s[14:15]
	s_mov_b32 m0, s65
	s_add_i32 s66, s57, 0xa000
	global_load_lds_dwordx4 v[0:1], off
	v_lshl_add_u64 v[0:1], v[2:3], 0, s[14:15]
	s_add_u32 s14, s28, 0x40080
	s_mov_b32 m0, s66
	s_addc_u32 s15, s29, 0
	global_load_lds_dwordx4 v[0:1], off
	s_add_i32 m0, s57, 0x1c000
	v_lshl_add_u64 v[0:1], s[14:15], 0, v[128:129]
	global_load_lds_dwordx4 v[0:1], off
	v_lshl_add_u64 v[0:1], s[14:15], 0, v[130:131]
	s_add_i32 m0, s57, 0x1e000
	v_and_b32_e32 v2, 15, v10
	global_load_lds_dwordx4 v[0:1], off
	v_bfe_u32 v1, v10, 4, 2
	v_lshlrev_b32_e32 v136, 4, v1
	v_lshl_or_b32 v153, s8, 6, v2
	v_lshlrev_b32_e32 v0, 3, v1
	v_lshl_or_b32 v1, v2, 6, v136
	v_lshlrev_b32_e32 v2, 2, v10
	v_and_b32_e32 v2, 32, v2
	v_bitop3_b32 v4, v1, s16, v2 bitop3:0xde
	v_bitop3_b32 v157, v1, s18, v2 bitop3:0xde
	v_mov_b32_e32 v137, 0
	v_lshlrev_b32_e32 v1, 14, v13
	s_sext_i32_i8 s17, s0
	s_cmpk_lt_u32 s1, 0x100
	v_lshl_add_u64 v[2:3], s[76:77], 0, v[136:137]
	s_mov_b64 s[0:1], 0x2800000
	v_and_b32_e32 v1, 0xffff8000, v1
	v_lshl_add_u64 v[138:139], v[2:3], 0, s[0:1]
	v_lshl_add_u32 v1, v12, 11, v1
	v_and_b32_e32 v2, 1, v13
	v_lshl_or_b32 v1, v2, 6, v1
	v_lshl_add_u32 v136, v14, 1, v1
	v_lshlrev_b32_e32 v1, 14, v8
	v_and_b32_e32 v1, 0xffff8000, v1
	v_lshl_add_u32 v1, v9, 11, v1
	v_and_b32_e32 v2, 1, v8
	s_mov_b64 s[18:19], 0x40080
	s_waitcnt vmcnt(6)
	v_lshl_or_b32 v1, v2, 6, v1
	v_lshl_add_u64 v[140:141], v[136:137], 0, s[18:19]
	v_lshl_add_u32 v136, v11, 1, v1
	s_cselect_b64 s[14:15], -1, 0
	s_ashr_i32 s67, s3, 31
	v_lshl_add_u64 v[142:143], v[136:137], 0, s[18:19]
	v_mov_b64_e32 v[144:145], 0xb00
	v_mov_b64_e32 v[146:147], 0xaff
	s_add_i32 s68, 0, 0x10000
	s_add_i32 s69, 0, 0x14000
	v_add_u32_e32 v161, 0, v4
	v_mov_b32_e32 v165, 0x358637bd
	s_movk_i32 s70, 0x1600
	s_lshl_b32 s16, s20, 1
	v_lshlrev_b32_e32 v136, 1, v0
	s_mov_b32 s71, 0
	s_barrier
	s_branch .LBB0_803

.LBB0_879:
	s_andn2_b64 vcc, exec, s[0:1]
	s_cbranch_vccnz .LBB0_925
	v_ashrrev_i32_e32 v1, 31, v8
	v_lshrrev_b32_e32 v1, 26, v1
	v_add_u32_e32 v1, v8, v1
	v_ashrrev_i32_e32 v9, 6, v1
	v_bfe_i32 v1, v8, 27, 1
	v_lshlrev_b32_e32 v0, 4, v8
	v_lshrrev_b32_e32 v1, 22, v1
	v_add_u32_e32 v1, v0, v1
	v_and_b32_e32 v1, 0xfffffc00, v1
	v_sub_u32_e32 v1, v0, v1
	v_lshrrev_b32_e32 v2, 4, v1
	v_bitop3_b32 v2, v2, v1, 32 bitop3:0x6c
	v_ashrrev_i32_e32 v1, 31, v1
	v_lshrrev_b32_e32 v1, 26, v1
	v_lshlrev_b32_e32 v3, 3, v9
	v_add_u32_e32 v1, v2, v1
	v_and_b32_e32 v3, -16, v3
	v_ashrrev_i32_e32 v11, 6, v1
	v_add_u32_e32 v1, v11, v3
	v_lshlrev_b32_e32 v3, 5, v9
	v_and_b32_e32 v10, 32, v3
	v_mul_i32_i24_e32 v3, 64, v11
	v_sub_u32_e32 v2, v2, v3
	v_mov_b32_e32 v3, 1
	v_ashrrev_i16_sdwa v2, v3, sext(v2) dst_sel:DWORD dst_unused:UNUSED_PAD src0_sel:DWORD src1_sel:BYTE_0
	s_waitcnt vmcnt(8)
	v_lshlrev_b32_e32 v4, 1, v1
	v_lshrrev_b32_e32 v5, 2, v1
	v_and_b32_e32 v6, 3, v11
	s_mov_b32 s1, 0xffffe0
	v_bfe_i32 v12, v2, 0, 16
	v_and_b32_e32 v4, 24, v4
	v_and_b32_e32 v5, 4, v5
	v_and_or_b32 v6, v1, s1, v6
	s_movk_i32 s4, 0xb00
	v_add_u32_e32 v2, v10, v12
	v_or3_b32 v4, v6, v5, v4
	v_mul_lo_u32 v1, v1, s4
	v_add_lshl_u32 v136, v2, v1, 1
	v_mul_u32_u24_e32 v1, 0xb00, v4
	v_add_u32_e32 v0, 0x2000, v0
	v_add_lshl_u32 v138, v1, v2, 1
	v_ashrrev_i32_e32 v1, 31, v0
	v_lshrrev_b32_e32 v1, 22, v1
	v_add_u32_e32 v1, v0, v1
	v_ashrrev_i32_e32 v13, 10, v1
	v_mul_i32_i24_e32 v1, 0x400, v13
	v_sub_u32_e32 v0, v0, v1
	v_lshrrev_b32_e32 v1, 4, v0
	v_bitop3_b32 v0, v1, v0, 32 bitop3:0x6c
	v_ashrrev_i32_e32 v2, 31, v0
	s_and_b32 s100, s2, 7
	s_mul_i32 s100, s100, 0x1600000
	s_add_u32 s100, s100, 0x8400000
	s_cmp_eq_u32 s99, 0
	s_cselect_b32 s100, 0xbc00000, s100
	s_add_u32 s42, s76, s100
	v_lshrrev_b32_e32 v2, 26, v2
	s_addc_u32 s43, s77, 0
	v_lshlrev_b32_e32 v1, 3, v13
	v_add_u32_e32 v2, v0, v2
	s_add_u32 s48, s76, 0x1b00000
	v_and_b32_e32 v1, -16, v1
	v_ashrrev_i32_e32 v14, 6, v2
	v_lshlrev_b32_e32 v4, 5, v13
	s_addc_u32 s49, s77, 0
	s_ashr_i32 s0, s6, 6
	v_add_u32_e32 v1, v14, v1
	v_and_b32_e32 v15, 32, v4
	v_and_b32_e32 v2, 0xc0, v2
	v_and_b32_e32 v4, 3, v14
	v_sub_u32_e32 v0, v0, v2
	v_and_or_b32 v4, v1, s1, v4
	s_ashr_i32 s1, s6, 8
	s_lshl_b32 s50, s0, 10
	s_mul_i32 s30, s17, 0x160000
	v_ashrrev_i16_sdwa v0, v3, sext(v0) dst_sel:DWORD dst_unused:UNUSED_PAD src0_sel:DWORD src1_sel:BYTE_0
	v_lshlrev_b32_e32 v2, 1, v1
	v_lshrrev_b32_e32 v3, 2, v1
	s_mul_hi_i32 s31, s17, 0x160000
	s_add_u32 s24, s48, s30
	v_bfe_i32 v16, v0, 0, 16
	v_and_b32_e32 v2, 24, v2
	v_and_b32_e32 v3, 4, v3
	s_addc_u32 s25, s49, s31
	s_add_i32 s51, s50, 0
	v_add_u32_e32 v0, v15, v16
	v_or3_b32 v2, v4, v3, v2
	v_mul_lo_u32 v1, v1, s4
	s_add_i32 m0, s51, 0x10000
	v_add_lshl_u32 v140, v0, v1, 1
	v_mul_u32_u24_e32 v1, 0xb00, v2
	global_load_lds_dwordx4 v138, s[24:25]
	s_add_i32 m0, s51, 0x12000
	v_add_lshl_u32 v142, v1, v0, 1
	s_add_u32 s8, s24, 0xb0000
	global_load_lds_dwordx4 v142, s[24:25]
	s_addc_u32 s9, s25, 0
	s_add_i32 m0, s51, 0x14000
	s_mul_i32 s28, s69, 0x160000
	global_load_lds_dwordx4 v138, s[8:9]
	s_add_i32 m0, s51, 0x16000
	s_mul_hi_i32 s29, s69, 0x160000
	s_add_u32 s26, s42, s28
	s_addc_u32 s27, s43, s29
	s_add_i32 s52, s51, 0x2000
	global_load_lds_dwordx4 v142, s[8:9]
	s_mov_b32 m0, s51
	s_add_u32 s8, s26, 0xb0000
	global_load_lds_dwordx4 v136, s[26:27]
	s_mov_b32 m0, s52
	s_addc_u32 s9, s27, 0
	s_add_i32 s53, s51, 0x4000
	global_load_lds_dwordx4 v140, s[26:27]
	s_mov_b32 m0, s53
	s_add_i32 s54, s51, 0x6000
	global_load_lds_dwordx4 v136, s[8:9]
	s_mov_b32 m0, s54
	v_mov_b32_e32 v145, 0
	global_load_lds_dwordx4 v140, s[8:9]
	v_mov_b32_e32 v139, v145
	v_mov_b32_e32 v143, v145
	v_mov_b32_e32 v137, v145
	v_mov_b32_e32 v141, v145
	s_cmp_eq_u32 s1, 1
	s_mov_b32 s9, 0
	v_lshl_add_u64 v[6:7], s[24:25], 0, v[138:139]
	v_lshl_add_u64 v[4:5], s[24:25], 0, v[142:143]
	v_lshl_add_u64 v[0:1], s[26:27], 0, v[136:137]
	s_cselect_b64 s[10:11], -1, 0
	s_cmp_lg_u32 s1, 1
	v_lshl_add_u64 v[2:3], s[26:27], 0, v[140:141]
	s_cbranch_scc1 .LBB0_882
	s_barrier

.LBB0_925:
	s_cmp_eq_u32 s99, 0
	s_cbranch_scc1 .Lfull_6
	s_waitcnt vmcnt(0) lgkmcnt(0)
	s_barrier
	s_cmp_lg_u32 s33, 0
	s_cbranch_scc1 .Lls_join_6
	s_mov_b64 exec, 1
	s_add_i32 s98, 0, 0x25fd0
	v_mov_b32_e32 v0, s98
	ds_read_b32 v2, v0
	s_getreg_b32 s98, hwreg(HW_REG_XCC_ID, 0, 4)
	s_and_b32 s98, s98, 15
	s_lshl_b32 s98, s98, 8
	s_add_u32 s100, s76, s98
	s_addc_u32 s101, s77, 0
	v_mov_b32_e32 v0, 0xc000
	v_mov_b32_e32 v1, 1
	global_atomic_add v0, v1, s[100:101]
	s_waitcnt lgkmcnt(0)
	v_mul_lo_u32 v2, v2, 6
	s_mov_b32 s98, 0

.LBB0_978:
	s_cmp_lg_u32 s27, 7
	s_cselect_b64 s[0:1], -1, 0
	s_and_b64 s[0:1], s[54:55], s[0:1]
	s_and_b64 vcc, exec, s[0:1]
	s_cbranch_vccnz .LBB0_1031
	v_mov_b32_e32 v0, 0
	s_and_b32 s100, s2, 7
	s_mul_i32 s100, s100, 0x2400000
	s_add_u32 s100, s100, 0x9a00000
	s_cmp_eq_u32 s99, 0
	s_cselect_b32 s100, 0x16c00000, s100
	s_add_u32 s4, s76, s100
	v_mbcnt_lo_u32_b32 v0, -1, v0
	s_addc_u32 s5, s77, 0
	v_mbcnt_hi_u32_b32 v0, -1, v0
	s_waitcnt vmcnt(19)
	v_add_u32_e32 v8, s33, v0
	s_cmpk_lt_i32 s2, 0x200
	v_mov_b32_e32 v142, 0
	s_cselect_b64 s[6:7], -1, 0
	s_cmpk_gt_i32 s2, 0x1ff
	v_readfirstlane_b32 s14, v8
	s_cbranch_scc1 .LBB0_1001
	s_ashr_i32 s8, s2, 31
	s_lshr_b32 s0, s8, 29
	s_add_i32 s10, s2, s0
	s_and_b32 s0, s10, -8
	s_sub_i32 s11, s2, s0
	s_cmp_gt_i32 s11, -1
	s_cbranch_scc0 .LBB0_982
	s_lshl_b32 s9, s11, 6
	s_cbranch_execz .LBB0_983
	s_branch .LBB0_984
